# speedup vs baseline: 1.0112x; 1.0112x over previous
; __device__ __forceinline__ float silu_f(float v) { return v * __builtin_amdgcn_rcpf(1.f + __expf(-v)); }
; __device__ __forceinline__ void gemm_tile(const TileDesc& td, char* shm_c, const int wv) {
;     ...
;   if (mode == EPI_PLAIN || mode == EPI_SILU) {
;     #pragma unroll
;     for (int ai = 0; ai < 2; ++ai)
;     #pragma unroll
;     for (int bj = 0; bj < 2; ++bj)
;     #pragma unroll
;     for (int m = 0; m < 4; ++m)
;     #pragma unroll
;     for (int n = 0; n < 2; ++n) {
;       f32x4 v = acc[ai][bj][m][n];
;       if (mode == EPI_SILU) { v[0] = silu_f(v[0]); v[1] = silu_f(v[1]); v[2] = silu_f(v[2]); v[3] = silu_f(v[3]); }
;       long o = (long)(td.bcol + bj * 128 + n * 16 + br_l) * td.ldo + (td.brow + ai * 128 + m * 16 + ar_l);
;       uint2 pk; pk.x = pack2(v[0], v[1]); pk.y = pack2(v[2], v[3]);
;       *(uint2*)(td.outb + o) = pk;
;     }
.Lg3_ps:
	s_cmp_eq_u64 s[38:39], 0
	s_cbranch_scc1 .Lg3_ps_store
	v_mul_f32_e32 v146, 0xbfb8aa3b, v124
	v_mul_f32_e32 v147, 0xbfb8aa3b, v125
	v_mul_f32_e32 v148, 0xbfb8aa3b, v126
	v_mul_f32_e32 v149, 0xbfb8aa3b, v127
	v_exp_f32_e32 v146, v146
	v_exp_f32_e32 v147, v147
	v_exp_f32_e32 v148, v148
	v_exp_f32_e32 v149, v149
	v_add_f32_e32 v146, 1.0, v146
	v_add_f32_e32 v147, 1.0, v147
	v_add_f32_e32 v148, 1.0, v148
	v_add_f32_e32 v149, 1.0, v149
	v_rcp_f32_e32 v146, v146
	v_rcp_f32_e32 v147, v147
	v_rcp_f32_e32 v148, v148
	v_rcp_f32_e32 v149, v149
	s_nop 0
	v_pk_mul_f32 v[124:125], v[124:125], v[146:147]
	v_pk_mul_f32 v[126:127], v[126:127], v[148:149]
	v_mul_f32_e32 v146, 0xbfb8aa3b, v116
	v_mul_f32_e32 v147, 0xbfb8aa3b, v117
	v_mul_f32_e32 v148, 0xbfb8aa3b, v118
	v_mul_f32_e32 v149, 0xbfb8aa3b, v119
	v_exp_f32_e32 v146, v146
	v_exp_f32_e32 v147, v147
	v_exp_f32_e32 v148, v148
	v_exp_f32_e32 v149, v149
	v_add_f32_e32 v146, 1.0, v146
	v_add_f32_e32 v147, 1.0, v147
	v_add_f32_e32 v148, 1.0, v148
	v_add_f32_e32 v149, 1.0, v149
	v_rcp_f32_e32 v146, v146
	v_rcp_f32_e32 v147, v147
	v_rcp_f32_e32 v148, v148
	v_rcp_f32_e32 v149, v149
	s_nop 0
	v_pk_mul_f32 v[116:117], v[116:117], v[146:147]
	v_pk_mul_f32 v[118:119], v[118:119], v[148:149]
	v_mul_f32_e32 v146, 0xbfb8aa3b, v108
	v_mul_f32_e32 v147, 0xbfb8aa3b, v109
	v_mul_f32_e32 v148, 0xbfb8aa3b, v110
	v_mul_f32_e32 v149, 0xbfb8aa3b, v111
	v_exp_f32_e32 v146, v146
	v_exp_f32_e32 v147, v147
	v_exp_f32_e32 v148, v148
	v_exp_f32_e32 v149, v149
	v_add_f32_e32 v146, 1.0, v146
	v_add_f32_e32 v147, 1.0, v147
	v_add_f32_e32 v148, 1.0, v148
	v_add_f32_e32 v149, 1.0, v149
	v_rcp_f32_e32 v146, v146
	v_rcp_f32_e32 v147, v147
	v_rcp_f32_e32 v148, v148
	v_rcp_f32_e32 v149, v149
	s_nop 0
	v_pk_mul_f32 v[108:109], v[108:109], v[146:147]
	v_pk_mul_f32 v[110:111], v[110:111], v[148:149]
	v_mul_f32_e32 v146, 0xbfb8aa3b, v100
	v_mul_f32_e32 v147, 0xbfb8aa3b, v101
	v_mul_f32_e32 v148, 0xbfb8aa3b, v102
	v_mul_f32_e32 v149, 0xbfb8aa3b, v103
	v_exp_f32_e32 v146, v146
	v_exp_f32_e32 v147, v147
	v_exp_f32_e32 v148, v148
	v_exp_f32_e32 v149, v149
	v_add_f32_e32 v146, 1.0, v146
	v_add_f32_e32 v147, 1.0, v147
	v_add_f32_e32 v148, 1.0, v148
	v_add_f32_e32 v149, 1.0, v149
	v_rcp_f32_e32 v146, v146
	v_rcp_f32_e32 v147, v147
	v_rcp_f32_e32 v148, v148
	v_rcp_f32_e32 v149, v149
	s_nop 0
	v_pk_mul_f32 v[100:101], v[100:101], v[146:147]
	v_pk_mul_f32 v[102:103], v[102:103], v[148:149]
	v_mul_f32_e32 v146, 0xbfb8aa3b, v120
	v_mul_f32_e32 v147, 0xbfb8aa3b, v121
	v_mul_f32_e32 v148, 0xbfb8aa3b, v122
	v_mul_f32_e32 v149, 0xbfb8aa3b, v123
	v_exp_f32_e32 v146, v146
	v_exp_f32_e32 v147, v147
	v_exp_f32_e32 v148, v148
	v_exp_f32_e32 v149, v149
	v_add_f32_e32 v146, 1.0, v146
	v_add_f32_e32 v147, 1.0, v147
	v_add_f32_e32 v148, 1.0, v148
	v_add_f32_e32 v149, 1.0, v149
	v_rcp_f32_e32 v146, v146
	v_rcp_f32_e32 v147, v147
	v_rcp_f32_e32 v148, v148
	v_rcp_f32_e32 v149, v149
	s_nop 0
	v_pk_mul_f32 v[120:121], v[120:121], v[146:147]
	v_pk_mul_f32 v[122:123], v[122:123], v[148:149]
	v_mul_f32_e32 v146, 0xbfb8aa3b, v112
	v_mul_f32_e32 v147, 0xbfb8aa3b, v113
	v_mul_f32_e32 v148, 0xbfb8aa3b, v114
	v_mul_f32_e32 v149, 0xbfb8aa3b, v115
	v_exp_f32_e32 v146, v146
	v_exp_f32_e32 v147, v147
	v_exp_f32_e32 v148, v148
	v_exp_f32_e32 v149, v149
	v_add_f32_e32 v146, 1.0, v146
	v_add_f32_e32 v147, 1.0, v147
	v_add_f32_e32 v148, 1.0, v148
	v_add_f32_e32 v149, 1.0, v149
	v_rcp_f32_e32 v146, v146
	v_rcp_f32_e32 v147, v147
	v_rcp_f32_e32 v148, v148
	v_rcp_f32_e32 v149, v149
	s_nop 0
	v_pk_mul_f32 v[112:113], v[112:113], v[146:147]
	v_pk_mul_f32 v[114:115], v[114:115], v[148:149]
	v_mul_f32_e32 v146, 0xbfb8aa3b, v104
	v_mul_f32_e32 v147, 0xbfb8aa3b, v105
	v_mul_f32_e32 v148, 0xbfb8aa3b, v106
	v_mul_f32_e32 v149, 0xbfb8aa3b, v107
	v_exp_f32_e32 v146, v146
	v_exp_f32_e32 v147, v147
	v_exp_f32_e32 v148, v148
	v_exp_f32_e32 v149, v149
	v_add_f32_e32 v146, 1.0, v146
	v_add_f32_e32 v147, 1.0, v147
	v_add_f32_e32 v148, 1.0, v148
	v_add_f32_e32 v149, 1.0, v149
	v_rcp_f32_e32 v146, v146
	v_rcp_f32_e32 v147, v147
	v_rcp_f32_e32 v148, v148
	v_rcp_f32_e32 v149, v149
	s_nop 0
	v_pk_mul_f32 v[104:105], v[104:105], v[146:147]
	v_pk_mul_f32 v[106:107], v[106:107], v[148:149]
	v_mul_f32_e32 v146, 0xbfb8aa3b, v96
	v_mul_f32_e32 v147, 0xbfb8aa3b, v97
	v_mul_f32_e32 v148, 0xbfb8aa3b, v98
	v_mul_f32_e32 v149, 0xbfb8aa3b, v99
	v_exp_f32_e32 v146, v146
	v_exp_f32_e32 v147, v147
	v_exp_f32_e32 v148, v148
	v_exp_f32_e32 v149, v149
	v_add_f32_e32 v146, 1.0, v146
	v_add_f32_e32 v147, 1.0, v147
	v_add_f32_e32 v148, 1.0, v148
	v_add_f32_e32 v149, 1.0, v149
	v_rcp_f32_e32 v146, v146
	v_rcp_f32_e32 v147, v147
	v_rcp_f32_e32 v148, v148
	v_rcp_f32_e32 v149, v149
	s_nop 0
	v_pk_mul_f32 v[96:97], v[96:97], v[146:147]
	v_pk_mul_f32 v[98:99], v[98:99], v[148:149]
	v_mul_f32_e32 v146, 0xbfb8aa3b, v92
	v_mul_f32_e32 v147, 0xbfb8aa3b, v93
	v_mul_f32_e32 v148, 0xbfb8aa3b, v94
	v_mul_f32_e32 v149, 0xbfb8aa3b, v95
	v_exp_f32_e32 v146, v146
	v_exp_f32_e32 v147, v147
	v_exp_f32_e32 v148, v148
	v_exp_f32_e32 v149, v149
	v_add_f32_e32 v146, 1.0, v146
	v_add_f32_e32 v147, 1.0, v147
	v_add_f32_e32 v148, 1.0, v148
	v_add_f32_e32 v149, 1.0, v149
	v_rcp_f32_e32 v146, v146
	v_rcp_f32_e32 v147, v147
	v_rcp_f32_e32 v148, v148
	v_rcp_f32_e32 v149, v149
	s_nop 0
	v_pk_mul_f32 v[92:93], v[92:93], v[146:147]
	v_pk_mul_f32 v[94:95], v[94:95], v[148:149]
	v_mul_f32_e32 v146, 0xbfb8aa3b, v84
	v_mul_f32_e32 v147, 0xbfb8aa3b, v85
	v_mul_f32_e32 v148, 0xbfb8aa3b, v86
	v_mul_f32_e32 v149, 0xbfb8aa3b, v87
	v_exp_f32_e32 v146, v146
	v_exp_f32_e32 v147, v147
	v_exp_f32_e32 v148, v148
	v_exp_f32_e32 v149, v149
	v_add_f32_e32 v146, 1.0, v146
; __device__ __forceinline__ float silu_f(float v) { return v * __builtin_amdgcn_rcpf(1.f + __expf(-v)); }
; __device__ __forceinline__ void gemm_tile(const TileDesc& td, char* shm_c, const int wv) {
;     ...
;     for (int m = 0; m < 4; ++m)
;     #pragma unroll
;     for (int n = 0; n < 2; ++n) {
;       f32x4 v = acc[ai][bj][m][n];
;       if (mode == EPI_SILU) { v[0] = silu_f(v[0]); v[1] = silu_f(v[1]); v[2] = silu_f(v[2]); v[3] = silu_f(v[3]); }
	v_add_f32_e32 v147, 1.0, v147
	v_add_f32_e32 v148, 1.0, v148
	v_add_f32_e32 v149, 1.0, v149
	v_rcp_f32_e32 v146, v146
	v_rcp_f32_e32 v147, v147
	v_rcp_f32_e32 v148, v148
	v_rcp_f32_e32 v149, v149
	s_nop 0
	v_pk_mul_f32 v[84:85], v[84:85], v[146:147]
	v_pk_mul_f32 v[86:87], v[86:87], v[148:149]
	v_mul_f32_e32 v146, 0xbfb8aa3b, v76
	v_mul_f32_e32 v147, 0xbfb8aa3b, v77
	v_mul_f32_e32 v148, 0xbfb8aa3b, v78
	v_mul_f32_e32 v149, 0xbfb8aa3b, v79
	v_exp_f32_e32 v146, v146
	v_exp_f32_e32 v147, v147
	v_exp_f32_e32 v148, v148
	v_exp_f32_e32 v149, v149
	v_add_f32_e32 v146, 1.0, v146
	v_add_f32_e32 v147, 1.0, v147
	v_add_f32_e32 v148, 1.0, v148
	v_add_f32_e32 v149, 1.0, v149
	v_rcp_f32_e32 v146, v146
	v_rcp_f32_e32 v147, v147
	v_rcp_f32_e32 v148, v148
	v_rcp_f32_e32 v149, v149
	s_nop 0
	v_pk_mul_f32 v[76:77], v[76:77], v[146:147]
	v_pk_mul_f32 v[78:79], v[78:79], v[148:149]
	v_mul_f32_e32 v146, 0xbfb8aa3b, v68
	v_mul_f32_e32 v147, 0xbfb8aa3b, v69
	v_mul_f32_e32 v148, 0xbfb8aa3b, v70
	v_mul_f32_e32 v149, 0xbfb8aa3b, v71
	v_exp_f32_e32 v146, v146
	v_exp_f32_e32 v147, v147
	v_exp_f32_e32 v148, v148
	v_exp_f32_e32 v149, v149
	v_add_f32_e32 v146, 1.0, v146
	v_add_f32_e32 v147, 1.0, v147
	v_add_f32_e32 v148, 1.0, v148
	v_add_f32_e32 v149, 1.0, v149
	v_rcp_f32_e32 v146, v146
	v_rcp_f32_e32 v147, v147
	v_rcp_f32_e32 v148, v148
	v_rcp_f32_e32 v149, v149
	s_nop 0
	v_pk_mul_f32 v[68:69], v[68:69], v[146:147]
	v_pk_mul_f32 v[70:71], v[70:71], v[148:149]
	v_mul_f32_e32 v146, 0xbfb8aa3b, v88
	v_mul_f32_e32 v147, 0xbfb8aa3b, v89
	v_mul_f32_e32 v148, 0xbfb8aa3b, v90
	v_mul_f32_e32 v149, 0xbfb8aa3b, v91
	v_exp_f32_e32 v146, v146
	v_exp_f32_e32 v147, v147
	v_exp_f32_e32 v148, v148
	v_exp_f32_e32 v149, v149
	v_add_f32_e32 v146, 1.0, v146
	v_add_f32_e32 v147, 1.0, v147
	v_add_f32_e32 v148, 1.0, v148
	v_add_f32_e32 v149, 1.0, v149
	v_rcp_f32_e32 v146, v146
	v_rcp_f32_e32 v147, v147
	v_rcp_f32_e32 v148, v148
	v_rcp_f32_e32 v149, v149
	s_nop 0
	v_pk_mul_f32 v[88:89], v[88:89], v[146:147]
	v_pk_mul_f32 v[90:91], v[90:91], v[148:149]
	v_mul_f32_e32 v146, 0xbfb8aa3b, v80
	v_mul_f32_e32 v147, 0xbfb8aa3b, v81
	v_mul_f32_e32 v148, 0xbfb8aa3b, v82
	v_mul_f32_e32 v149, 0xbfb8aa3b, v83
	v_exp_f32_e32 v146, v146
	v_exp_f32_e32 v147, v147
	v_exp_f32_e32 v148, v148
	v_exp_f32_e32 v149, v149
	v_add_f32_e32 v146, 1.0, v146
	v_add_f32_e32 v147, 1.0, v147
	v_add_f32_e32 v148, 1.0, v148
	v_add_f32_e32 v149, 1.0, v149
	v_rcp_f32_e32 v146, v146
	v_rcp_f32_e32 v147, v147
	v_rcp_f32_e32 v148, v148
	v_rcp_f32_e32 v149, v149
	s_nop 0
	v_pk_mul_f32 v[80:81], v[80:81], v[146:147]
	v_pk_mul_f32 v[82:83], v[82:83], v[148:149]
	v_mul_f32_e32 v146, 0xbfb8aa3b, v72
	v_mul_f32_e32 v147, 0xbfb8aa3b, v73
	v_mul_f32_e32 v148, 0xbfb8aa3b, v74
	v_mul_f32_e32 v149, 0xbfb8aa3b, v75
	v_exp_f32_e32 v146, v146
	v_exp_f32_e32 v147, v147
	v_exp_f32_e32 v148, v148
	v_exp_f32_e32 v149, v149
	v_add_f32_e32 v146, 1.0, v146
	v_add_f32_e32 v147, 1.0, v147
	v_add_f32_e32 v148, 1.0, v148
	v_add_f32_e32 v149, 1.0, v149
	v_rcp_f32_e32 v146, v146
	v_rcp_f32_e32 v147, v147
	v_rcp_f32_e32 v148, v148
	v_rcp_f32_e32 v149, v149
	s_nop 0
	v_pk_mul_f32 v[72:73], v[72:73], v[146:147]
	v_pk_mul_f32 v[74:75], v[74:75], v[148:149]
	v_mul_f32_e32 v146, 0xbfb8aa3b, v64
	v_mul_f32_e32 v147, 0xbfb8aa3b, v65
	v_mul_f32_e32 v148, 0xbfb8aa3b, v66
	v_mul_f32_e32 v149, 0xbfb8aa3b, v67
	v_exp_f32_e32 v146, v146
	v_exp_f32_e32 v147, v147
	v_exp_f32_e32 v148, v148
	v_exp_f32_e32 v149, v149
	v_add_f32_e32 v146, 1.0, v146
	v_add_f32_e32 v147, 1.0, v147
	v_add_f32_e32 v148, 1.0, v148
	v_add_f32_e32 v149, 1.0, v149
	v_rcp_f32_e32 v146, v146
	v_rcp_f32_e32 v147, v147
	v_rcp_f32_e32 v148, v148
	v_rcp_f32_e32 v149, v149
	s_nop 0
	v_pk_mul_f32 v[64:65], v[64:65], v[146:147]
	v_pk_mul_f32 v[66:67], v[66:67], v[148:149]
	v_mul_f32_e32 v146, 0xbfb8aa3b, v60
	v_mul_f32_e32 v147, 0xbfb8aa3b, v61
	v_mul_f32_e32 v148, 0xbfb8aa3b, v62
	v_mul_f32_e32 v149, 0xbfb8aa3b, v63
	v_exp_f32_e32 v146, v146
	v_exp_f32_e32 v147, v147
	v_exp_f32_e32 v148, v148
	v_exp_f32_e32 v149, v149
	v_add_f32_e32 v146, 1.0, v146
	v_add_f32_e32 v147, 1.0, v147
	v_add_f32_e32 v148, 1.0, v148
	v_add_f32_e32 v149, 1.0, v149
	v_rcp_f32_e32 v146, v146
	v_rcp_f32_e32 v147, v147
	v_rcp_f32_e32 v148, v148
	v_rcp_f32_e32 v149, v149
	s_nop 0
	v_pk_mul_f32 v[60:61], v[60:61], v[146:147]
	v_pk_mul_f32 v[62:63], v[62:63], v[148:149]
	v_mul_f32_e32 v146, 0xbfb8aa3b, v52
	v_mul_f32_e32 v147, 0xbfb8aa3b, v53
	v_mul_f32_e32 v148, 0xbfb8aa3b, v54
	v_mul_f32_e32 v149, 0xbfb8aa3b, v55
	v_exp_f32_e32 v146, v146
	v_exp_f32_e32 v147, v147
	v_exp_f32_e32 v148, v148
	v_exp_f32_e32 v149, v149
	v_add_f32_e32 v146, 1.0, v146
	v_add_f32_e32 v147, 1.0, v147
	v_add_f32_e32 v148, 1.0, v148
	v_add_f32_e32 v149, 1.0, v149
	v_rcp_f32_e32 v146, v146
	v_rcp_f32_e32 v147, v147
	v_rcp_f32_e32 v148, v148
	v_rcp_f32_e32 v149, v149
	s_nop 0
	v_pk_mul_f32 v[52:53], v[52:53], v[146:147]
	v_pk_mul_f32 v[54:55], v[54:55], v[148:149]
	v_mul_f32_e32 v146, 0xbfb8aa3b, v44
	v_mul_f32_e32 v147, 0xbfb8aa3b, v45
	v_mul_f32_e32 v148, 0xbfb8aa3b, v46
	v_mul_f32_e32 v149, 0xbfb8aa3b, v47
	v_exp_f32_e32 v146, v146
	v_exp_f32_e32 v147, v147
	v_exp_f32_e32 v148, v148
	v_exp_f32_e32 v149, v149
	v_add_f32_e32 v146, 1.0, v146
	v_add_f32_e32 v147, 1.0, v147
	v_add_f32_e32 v148, 1.0, v148
	v_add_f32_e32 v149, 1.0, v149
	v_rcp_f32_e32 v146, v146
	v_rcp_f32_e32 v147, v147
	v_rcp_f32_e32 v148, v148
	v_rcp_f32_e32 v149, v149
	s_nop 0
	v_pk_mul_f32 v[44:45], v[44:45], v[146:147]
	v_pk_mul_f32 v[46:47], v[46:47], v[148:149]
	v_mul_f32_e32 v146, 0xbfb8aa3b, v36
	v_mul_f32_e32 v147, 0xbfb8aa3b, v37
	v_mul_f32_e32 v148, 0xbfb8aa3b, v38
	v_mul_f32_e32 v149, 0xbfb8aa3b, v39
; __device__ __forceinline__ float silu_f(float v) { return v * __builtin_amdgcn_rcpf(1.f + __expf(-v)); }
; __device__ __forceinline__ void gemm_tile(const TileDesc& td, char* shm_c, const int wv) {
;     ...
;     for (int m = 0; m < 4; ++m)
;     #pragma unroll
;     for (int n = 0; n < 2; ++n) {
;       f32x4 v = acc[ai][bj][m][n];
;       if (mode == EPI_SILU) { v[0] = silu_f(v[0]); v[1] = silu_f(v[1]); v[2] = silu_f(v[2]); v[3] = silu_f(v[3]); }
	v_exp_f32_e32 v146, v146
	v_exp_f32_e32 v147, v147
	v_exp_f32_e32 v148, v148
	v_exp_f32_e32 v149, v149
	v_add_f32_e32 v146, 1.0, v146
	v_add_f32_e32 v147, 1.0, v147
	v_add_f32_e32 v148, 1.0, v148
	v_add_f32_e32 v149, 1.0, v149
	v_rcp_f32_e32 v146, v146
	v_rcp_f32_e32 v147, v147
	v_rcp_f32_e32 v148, v148
	v_rcp_f32_e32 v149, v149
	s_nop 0
	v_pk_mul_f32 v[36:37], v[36:37], v[146:147]
	v_pk_mul_f32 v[38:39], v[38:39], v[148:149]
	v_mul_f32_e32 v146, 0xbfb8aa3b, v56
	v_mul_f32_e32 v147, 0xbfb8aa3b, v57
	v_mul_f32_e32 v148, 0xbfb8aa3b, v58
	v_mul_f32_e32 v149, 0xbfb8aa3b, v59
	v_exp_f32_e32 v146, v146
	v_exp_f32_e32 v147, v147
	v_exp_f32_e32 v148, v148
	v_exp_f32_e32 v149, v149
	v_add_f32_e32 v146, 1.0, v146
	v_add_f32_e32 v147, 1.0, v147
	v_add_f32_e32 v148, 1.0, v148
	v_add_f32_e32 v149, 1.0, v149
	v_rcp_f32_e32 v146, v146
	v_rcp_f32_e32 v147, v147
	v_rcp_f32_e32 v148, v148
	v_rcp_f32_e32 v149, v149
	s_nop 0
	v_pk_mul_f32 v[56:57], v[56:57], v[146:147]
	v_pk_mul_f32 v[58:59], v[58:59], v[148:149]
	v_mul_f32_e32 v146, 0xbfb8aa3b, v48
	v_mul_f32_e32 v147, 0xbfb8aa3b, v49
	v_mul_f32_e32 v148, 0xbfb8aa3b, v50
	v_mul_f32_e32 v149, 0xbfb8aa3b, v51
	v_exp_f32_e32 v146, v146
	v_exp_f32_e32 v147, v147
	v_exp_f32_e32 v148, v148
	v_exp_f32_e32 v149, v149
	v_add_f32_e32 v146, 1.0, v146
	v_add_f32_e32 v147, 1.0, v147
	v_add_f32_e32 v148, 1.0, v148
	v_add_f32_e32 v149, 1.0, v149
	v_rcp_f32_e32 v146, v146
	v_rcp_f32_e32 v147, v147
	v_rcp_f32_e32 v148, v148
	v_rcp_f32_e32 v149, v149
	s_nop 0
	v_pk_mul_f32 v[48:49], v[48:49], v[146:147]
	v_pk_mul_f32 v[50:51], v[50:51], v[148:149]
	v_mul_f32_e32 v146, 0xbfb8aa3b, v40
	v_mul_f32_e32 v147, 0xbfb8aa3b, v41
	v_mul_f32_e32 v148, 0xbfb8aa3b, v42
	v_mul_f32_e32 v149, 0xbfb8aa3b, v43
	v_exp_f32_e32 v146, v146
	v_exp_f32_e32 v147, v147
	v_exp_f32_e32 v148, v148
	v_exp_f32_e32 v149, v149
	v_add_f32_e32 v146, 1.0, v146
	v_add_f32_e32 v147, 1.0, v147
	v_add_f32_e32 v148, 1.0, v148
	v_add_f32_e32 v149, 1.0, v149
	v_rcp_f32_e32 v146, v146
	v_rcp_f32_e32 v147, v147
	v_rcp_f32_e32 v148, v148
	v_rcp_f32_e32 v149, v149
	s_nop 0
	v_pk_mul_f32 v[40:41], v[40:41], v[146:147]
	v_pk_mul_f32 v[42:43], v[42:43], v[148:149]
	v_mul_f32_e32 v146, 0xbfb8aa3b, v32
	v_mul_f32_e32 v147, 0xbfb8aa3b, v33
	v_mul_f32_e32 v148, 0xbfb8aa3b, v34
	v_mul_f32_e32 v149, 0xbfb8aa3b, v35
	v_exp_f32_e32 v146, v146
	v_exp_f32_e32 v147, v147
	v_exp_f32_e32 v148, v148
	v_exp_f32_e32 v149, v149
	v_add_f32_e32 v146, 1.0, v146
	v_add_f32_e32 v147, 1.0, v147
	v_add_f32_e32 v148, 1.0, v148
	v_add_f32_e32 v149, 1.0, v149
	v_rcp_f32_e32 v146, v146
	v_rcp_f32_e32 v147, v147
	v_rcp_f32_e32 v148, v148
	v_rcp_f32_e32 v149, v149
	s_nop 0
	v_pk_mul_f32 v[32:33], v[32:33], v[146:147]
	v_pk_mul_f32 v[34:35], v[34:35], v[148:149]
	v_mul_f32_e32 v146, 0xbfb8aa3b, v28
	v_mul_f32_e32 v147, 0xbfb8aa3b, v29
	v_mul_f32_e32 v148, 0xbfb8aa3b, v30
	v_mul_f32_e32 v149, 0xbfb8aa3b, v31
	v_exp_f32_e32 v146, v146
	v_exp_f32_e32 v147, v147
	v_exp_f32_e32 v148, v148
	v_exp_f32_e32 v149, v149
	v_add_f32_e32 v146, 1.0, v146
	v_add_f32_e32 v147, 1.0, v147
	v_add_f32_e32 v148, 1.0, v148
	v_add_f32_e32 v149, 1.0, v149
	v_rcp_f32_e32 v146, v146
	v_rcp_f32_e32 v147, v147
	v_rcp_f32_e32 v148, v148
	v_rcp_f32_e32 v149, v149
	s_nop 0
	v_pk_mul_f32 v[28:29], v[28:29], v[146:147]
	v_pk_mul_f32 v[30:31], v[30:31], v[148:149]
	v_mul_f32_e32 v146, 0xbfb8aa3b, v20
	v_mul_f32_e32 v147, 0xbfb8aa3b, v21
	v_mul_f32_e32 v148, 0xbfb8aa3b, v22
	v_mul_f32_e32 v149, 0xbfb8aa3b, v23
	v_exp_f32_e32 v146, v146
	v_exp_f32_e32 v147, v147
	v_exp_f32_e32 v148, v148
	v_exp_f32_e32 v149, v149
	v_add_f32_e32 v146, 1.0, v146
	v_add_f32_e32 v147, 1.0, v147
	v_add_f32_e32 v148, 1.0, v148
	v_add_f32_e32 v149, 1.0, v149
	v_rcp_f32_e32 v146, v146
	v_rcp_f32_e32 v147, v147
	v_rcp_f32_e32 v148, v148
	v_rcp_f32_e32 v149, v149
	s_nop 0
	v_pk_mul_f32 v[20:21], v[20:21], v[146:147]
	v_pk_mul_f32 v[22:23], v[22:23], v[148:149]
	v_mul_f32_e32 v146, 0xbfb8aa3b, v12
	v_mul_f32_e32 v147, 0xbfb8aa3b, v13
	v_mul_f32_e32 v148, 0xbfb8aa3b, v14
	v_mul_f32_e32 v149, 0xbfb8aa3b, v15
	v_exp_f32_e32 v146, v146
	v_exp_f32_e32 v147, v147
	v_exp_f32_e32 v148, v148
	v_exp_f32_e32 v149, v149
	v_add_f32_e32 v146, 1.0, v146
	v_add_f32_e32 v147, 1.0, v147
	v_add_f32_e32 v148, 1.0, v148
	v_add_f32_e32 v149, 1.0, v149
	v_rcp_f32_e32 v146, v146
	v_rcp_f32_e32 v147, v147
	v_rcp_f32_e32 v148, v148
	v_rcp_f32_e32 v149, v149
	s_nop 0
	v_pk_mul_f32 v[12:13], v[12:13], v[146:147]
	v_pk_mul_f32 v[14:15], v[14:15], v[148:149]
	v_mul_f32_e32 v146, 0xbfb8aa3b, v4
	v_mul_f32_e32 v147, 0xbfb8aa3b, v5
	v_mul_f32_e32 v148, 0xbfb8aa3b, v6
	v_mul_f32_e32 v149, 0xbfb8aa3b, v7
	v_exp_f32_e32 v146, v146
	v_exp_f32_e32 v147, v147
	v_exp_f32_e32 v148, v148
	v_exp_f32_e32 v149, v149
	v_add_f32_e32 v146, 1.0, v146
	v_add_f32_e32 v147, 1.0, v147
	v_add_f32_e32 v148, 1.0, v148
	v_add_f32_e32 v149, 1.0, v149
	v_rcp_f32_e32 v146, v146
	v_rcp_f32_e32 v147, v147
	v_rcp_f32_e32 v148, v148
	v_rcp_f32_e32 v149, v149
	s_nop 0
	v_pk_mul_f32 v[4:5], v[4:5], v[146:147]
	v_pk_mul_f32 v[6:7], v[6:7], v[148:149]
	v_mul_f32_e32 v146, 0xbfb8aa3b, v24
	v_mul_f32_e32 v147, 0xbfb8aa3b, v25
	v_mul_f32_e32 v148, 0xbfb8aa3b, v26
	v_mul_f32_e32 v149, 0xbfb8aa3b, v27
	v_exp_f32_e32 v146, v146
	v_exp_f32_e32 v147, v147
	v_exp_f32_e32 v148, v148
	v_exp_f32_e32 v149, v149
	v_add_f32_e32 v146, 1.0, v146
	v_add_f32_e32 v147, 1.0, v147
	v_add_f32_e32 v148, 1.0, v148
	v_add_f32_e32 v149, 1.0, v149
	v_rcp_f32_e32 v146, v146
	v_rcp_f32_e32 v147, v147
	v_rcp_f32_e32 v148, v148
	v_rcp_f32_e32 v149, v149
	s_nop 0
	v_pk_mul_f32 v[24:25], v[24:25], v[146:147]
	v_pk_mul_f32 v[26:27], v[26:27], v[148:149]
; __device__ __forceinline__ float silu_f(float v) { return v * __builtin_amdgcn_rcpf(1.f + __expf(-v)); }
; __device__ __forceinline__ void gemm_tile(const TileDesc& td, char* shm_c, const int wv) {
;     ...
;   if (mode == EPI_PLAIN || mode == EPI_SILU) {
;     #pragma unroll
;     for (int ai = 0; ai < 2; ++ai)
;     #pragma unroll
;     for (int bj = 0; bj < 2; ++bj)
;     #pragma unroll
;     for (int m = 0; m < 4; ++m)
;     #pragma unroll
;     for (int n = 0; n < 2; ++n) {
;       f32x4 v = acc[ai][bj][m][n];
;       if (mode == EPI_SILU) { v[0] = silu_f(v[0]); v[1] = silu_f(v[1]); v[2] = silu_f(v[2]); v[3] = silu_f(v[3]); }
;       long o = (long)(td.bcol + bj * 128 + n * 16 + br_l) * td.ldo + (td.brow + ai * 128 + m * 16 + ar_l);
;       uint2 pk; pk.x = pack2(v[0], v[1]); pk.y = pack2(v[2], v[3]);
;       *(uint2*)(td.outb + o) = pk;
;     }
	v_mul_f32_e32 v146, 0xbfb8aa3b, v16
	v_mul_f32_e32 v147, 0xbfb8aa3b, v17
	v_mul_f32_e32 v148, 0xbfb8aa3b, v18
	v_mul_f32_e32 v149, 0xbfb8aa3b, v19
	v_exp_f32_e32 v146, v146
	v_exp_f32_e32 v147, v147
	v_exp_f32_e32 v148, v148
	v_exp_f32_e32 v149, v149
	v_add_f32_e32 v146, 1.0, v146
	v_add_f32_e32 v147, 1.0, v147
	v_add_f32_e32 v148, 1.0, v148
	v_add_f32_e32 v149, 1.0, v149
	v_rcp_f32_e32 v146, v146
	v_rcp_f32_e32 v147, v147
	v_rcp_f32_e32 v148, v148
	v_rcp_f32_e32 v149, v149
	s_nop 0
	v_pk_mul_f32 v[16:17], v[16:17], v[146:147]
	v_pk_mul_f32 v[18:19], v[18:19], v[148:149]
	v_mul_f32_e32 v146, 0xbfb8aa3b, v8
	v_mul_f32_e32 v147, 0xbfb8aa3b, v9
	v_mul_f32_e32 v148, 0xbfb8aa3b, v10
	v_mul_f32_e32 v149, 0xbfb8aa3b, v11
	v_exp_f32_e32 v146, v146
	v_exp_f32_e32 v147, v147
	v_exp_f32_e32 v148, v148
	v_exp_f32_e32 v149, v149
	v_add_f32_e32 v146, 1.0, v146
	v_add_f32_e32 v147, 1.0, v147
	v_add_f32_e32 v148, 1.0, v148
	v_add_f32_e32 v149, 1.0, v149
	v_rcp_f32_e32 v146, v146
	v_rcp_f32_e32 v147, v147
	v_rcp_f32_e32 v148, v148
	v_rcp_f32_e32 v149, v149
	s_nop 0
	v_pk_mul_f32 v[8:9], v[8:9], v[146:147]
	v_pk_mul_f32 v[10:11], v[10:11], v[148:149]
	v_mul_f32_e32 v146, 0xbfb8aa3b, v0
	v_mul_f32_e32 v147, 0xbfb8aa3b, v1
	v_mul_f32_e32 v148, 0xbfb8aa3b, v2
	v_mul_f32_e32 v149, 0xbfb8aa3b, v3
	v_exp_f32_e32 v146, v146
	v_exp_f32_e32 v147, v147
	v_exp_f32_e32 v148, v148
	v_exp_f32_e32 v149, v149
	v_add_f32_e32 v146, 1.0, v146
	v_add_f32_e32 v147, 1.0, v147
	v_add_f32_e32 v148, 1.0, v148
	v_add_f32_e32 v149, 1.0, v149
	v_rcp_f32_e32 v146, v146
	v_rcp_f32_e32 v147, v147
	v_rcp_f32_e32 v148, v148
	v_rcp_f32_e32 v149, v149
	s_nop 0
	v_pk_mul_f32 v[0:1], v[0:1], v[146:147]
	v_pk_mul_f32 v[2:3], v[2:3], v[148:149]
.Lg3_ps_store:
	v_mbcnt_lo_u32_b32 v144, -1, 0
	v_mbcnt_hi_u32_b32 v144, -1, v144
	v_and_b32_e32 v144, 16, v144
	v_lshrrev_b32_e32 v145, 1, v144
	v_add_u32_e32 v144, v144, v145
	v_mov_b32_e32 v145, 0
	v_or_b32_e32 v130, s50, v164
	s_ashr_i32 s2, s50, 31
	v_mul_lo_u32 v128, s35, v130
	s_mul_i32 s4, s34, s2
	v_mad_u64_u32 v[134:135], s[2:3], s34, v130, 0
	v_add3_u32 v135, v135, s4, v128
	v_add_u32_e32 v128, s14, v136
	v_ashrrev_i32_e32 v129, 31, v128
	v_lshl_add_u64 v[138:139], v[134:135], 1, s[36:37]
	v_lshl_add_u64 v[140:141], v[128:129], 1, v[138:139]
	v_lshl_add_u64 v[142:143], v[140:141], 0, v[144:145]
	v_cvt_pk_bf16_f32 v124, v124, v125
	v_cvt_pk_bf16_f32 v125, v126, v127
	v_cvt_pk_bf16_f32 v126, v116, v117
	v_cvt_pk_bf16_f32 v127, v118, v119
	s_nop 1
	v_permlane16_swap_b32_e32 v124, v126
	v_permlane16_swap_b32_e32 v125, v127
	global_store_dwordx4 v[142:143], v[124:127], off
	v_cvt_pk_bf16_f32 v108, v108, v109
	v_cvt_pk_bf16_f32 v109, v110, v111
	v_cvt_pk_bf16_f32 v110, v100, v101
	v_cvt_pk_bf16_f32 v111, v102, v103
	s_nop 1
	v_permlane16_swap_b32_e32 v108, v110
	v_permlane16_swap_b32_e32 v109, v111
	global_store_dwordx4 v[142:143], v[108:111], off offset:64
	v_cvt_pk_bf16_f32 v60, v60, v61
	v_cvt_pk_bf16_f32 v61, v62, v63
	v_cvt_pk_bf16_f32 v62, v52, v53
	v_cvt_pk_bf16_f32 v63, v54, v55
	s_nop 1
	v_permlane16_swap_b32_e32 v60, v62
	v_permlane16_swap_b32_e32 v61, v63
	global_store_dwordx4 v[142:143], v[60:63], off offset:256
	v_cvt_pk_bf16_f32 v44, v44, v45
	v_cvt_pk_bf16_f32 v45, v46, v47
	v_cvt_pk_bf16_f32 v46, v36, v37
	v_cvt_pk_bf16_f32 v47, v38, v39
	s_nop 1
	v_permlane16_swap_b32_e32 v44, v46
	v_permlane16_swap_b32_e32 v45, v47
	global_store_dwordx4 v[142:143], v[44:47], off offset:320
	v_or_b32_e32 v130, s50, v164
	v_or_b32_e32 v130, 0x10, v130
	s_ashr_i32 s2, s50, 31
	v_mul_lo_u32 v128, s35, v130
	s_mul_i32 s4, s34, s2
	v_mad_u64_u32 v[134:135], s[2:3], s34, v130, 0
	v_add3_u32 v135, v135, s4, v128
	v_add_u32_e32 v128, s14, v136
	v_ashrrev_i32_e32 v129, 31, v128
	v_lshl_add_u64 v[138:139], v[134:135], 1, s[36:37]
	v_lshl_add_u64 v[140:141], v[128:129], 1, v[138:139]
	v_lshl_add_u64 v[142:143], v[140:141], 0, v[144:145]
	v_cvt_pk_bf16_f32 v120, v120, v121
	v_cvt_pk_bf16_f32 v121, v122, v123
	v_cvt_pk_bf16_f32 v122, v112, v113
	v_cvt_pk_bf16_f32 v123, v114, v115
	s_nop 1
	v_permlane16_swap_b32_e32 v120, v122
	v_permlane16_swap_b32_e32 v121, v123
	global_store_dwordx4 v[142:143], v[120:123], off
	v_cvt_pk_bf16_f32 v104, v104, v105
	v_cvt_pk_bf16_f32 v105, v106, v107
	v_cvt_pk_bf16_f32 v106, v96, v97
	v_cvt_pk_bf16_f32 v107, v98, v99
	s_nop 1
	v_permlane16_swap_b32_e32 v104, v106
	v_permlane16_swap_b32_e32 v105, v107
; __device__ __forceinline__ float silu_f(float v) { return v * __builtin_amdgcn_rcpf(1.f + __expf(-v)); }
; __device__ __forceinline__ void gemm_tile(const TileDesc& td, char* shm_c, const int wv) {
;     ...
;   if (mode == EPI_PLAIN || mode == EPI_SILU) {
;     #pragma unroll
;     for (int ai = 0; ai < 2; ++ai)
;     #pragma unroll
;     for (int bj = 0; bj < 2; ++bj)
;     #pragma unroll
;     for (int m = 0; m < 4; ++m)
;     #pragma unroll
;     for (int n = 0; n < 2; ++n) {
;       f32x4 v = acc[ai][bj][m][n];
;       if (mode == EPI_SILU) { v[0] = silu_f(v[0]); v[1] = silu_f(v[1]); v[2] = silu_f(v[2]); v[3] = silu_f(v[3]); }
;       long o = (long)(td.bcol + bj * 128 + n * 16 + br_l) * td.ldo + (td.brow + ai * 128 + m * 16 + ar_l);
;       uint2 pk; pk.x = pack2(v[0], v[1]); pk.y = pack2(v[2], v[3]);
;       *(uint2*)(td.outb + o) = pk;
;     }
	global_store_dwordx4 v[142:143], v[104:107], off offset:64
	v_cvt_pk_bf16_f32 v56, v56, v57
	v_cvt_pk_bf16_f32 v57, v58, v59
	v_cvt_pk_bf16_f32 v58, v48, v49
	v_cvt_pk_bf16_f32 v59, v50, v51
	s_nop 1
	v_permlane16_swap_b32_e32 v56, v58
	v_permlane16_swap_b32_e32 v57, v59
	global_store_dwordx4 v[142:143], v[56:59], off offset:256
	v_cvt_pk_bf16_f32 v40, v40, v41
	v_cvt_pk_bf16_f32 v41, v42, v43
	v_cvt_pk_bf16_f32 v42, v32, v33
	v_cvt_pk_bf16_f32 v43, v34, v35
	s_nop 1
	v_permlane16_swap_b32_e32 v40, v42
	v_permlane16_swap_b32_e32 v41, v43
	global_store_dwordx4 v[142:143], v[40:43], off offset:320
	v_or_b32_e32 v130, s50, v164
	v_or_b32_e32 v130, 0x80, v130
	s_ashr_i32 s2, s50, 31
	v_mul_lo_u32 v128, s35, v130
	s_mul_i32 s4, s34, s2
	v_mad_u64_u32 v[134:135], s[2:3], s34, v130, 0
	v_add3_u32 v135, v135, s4, v128
	v_add_u32_e32 v128, s14, v136
	v_ashrrev_i32_e32 v129, 31, v128
	v_lshl_add_u64 v[138:139], v[134:135], 1, s[36:37]
	v_lshl_add_u64 v[140:141], v[128:129], 1, v[138:139]
	v_lshl_add_u64 v[142:143], v[140:141], 0, v[144:145]
	v_cvt_pk_bf16_f32 v92, v92, v93
	v_cvt_pk_bf16_f32 v93, v94, v95
	v_cvt_pk_bf16_f32 v94, v84, v85
	v_cvt_pk_bf16_f32 v95, v86, v87
	s_nop 1
	v_permlane16_swap_b32_e32 v92, v94
	v_permlane16_swap_b32_e32 v93, v95
	global_store_dwordx4 v[142:143], v[92:95], off
	v_cvt_pk_bf16_f32 v76, v76, v77
	v_cvt_pk_bf16_f32 v77, v78, v79
	v_cvt_pk_bf16_f32 v78, v68, v69
	v_cvt_pk_bf16_f32 v79, v70, v71
	s_nop 1
	v_permlane16_swap_b32_e32 v76, v78
	v_permlane16_swap_b32_e32 v77, v79
	global_store_dwordx4 v[142:143], v[76:79], off offset:64
	v_cvt_pk_bf16_f32 v28, v28, v29
	v_cvt_pk_bf16_f32 v29, v30, v31
	v_cvt_pk_bf16_f32 v30, v20, v21
	v_cvt_pk_bf16_f32 v31, v22, v23
	s_nop 1
	v_permlane16_swap_b32_e32 v28, v30
	v_permlane16_swap_b32_e32 v29, v31
	global_store_dwordx4 v[142:143], v[28:31], off offset:256
	v_cvt_pk_bf16_f32 v12, v12, v13
	v_cvt_pk_bf16_f32 v13, v14, v15
	v_cvt_pk_bf16_f32 v14, v4, v5
	v_cvt_pk_bf16_f32 v15, v6, v7
	s_nop 1
	v_permlane16_swap_b32_e32 v12, v14
	v_permlane16_swap_b32_e32 v13, v15
	global_store_dwordx4 v[142:143], v[12:15], off offset:320
	v_or_b32_e32 v130, s50, v164
	v_or_b32_e32 v130, 0x90, v130
	s_ashr_i32 s2, s50, 31
	v_mul_lo_u32 v128, s35, v130
	s_mul_i32 s4, s34, s2
	v_mad_u64_u32 v[134:135], s[2:3], s34, v130, 0
	v_add3_u32 v135, v135, s4, v128
	v_add_u32_e32 v128, s14, v136
	v_ashrrev_i32_e32 v129, 31, v128
	v_lshl_add_u64 v[138:139], v[134:135], 1, s[36:37]
	v_lshl_add_u64 v[140:141], v[128:129], 1, v[138:139]
	v_lshl_add_u64 v[142:143], v[140:141], 0, v[144:145]
	v_cvt_pk_bf16_f32 v88, v88, v89
	v_cvt_pk_bf16_f32 v89, v90, v91
	v_cvt_pk_bf16_f32 v90, v80, v81
	v_cvt_pk_bf16_f32 v91, v82, v83
	s_nop 1
	v_permlane16_swap_b32_e32 v88, v90
	v_permlane16_swap_b32_e32 v89, v91
	global_store_dwordx4 v[142:143], v[88:91], off
	v_cvt_pk_bf16_f32 v72, v72, v73
	v_cvt_pk_bf16_f32 v73, v74, v75
	v_cvt_pk_bf16_f32 v74, v64, v65
	v_cvt_pk_bf16_f32 v75, v66, v67
	s_nop 1
	v_permlane16_swap_b32_e32 v72, v74
	v_permlane16_swap_b32_e32 v73, v75
	global_store_dwordx4 v[142:143], v[72:75], off offset:64
	v_cvt_pk_bf16_f32 v24, v24, v25
	v_cvt_pk_bf16_f32 v25, v26, v27
	v_cvt_pk_bf16_f32 v26, v16, v17
	v_cvt_pk_bf16_f32 v27, v18, v19
	s_nop 1
	v_permlane16_swap_b32_e32 v24, v26
	v_permlane16_swap_b32_e32 v25, v27
	global_store_dwordx4 v[142:143], v[24:27], off offset:256
	v_cvt_pk_bf16_f32 v8, v8, v9
	v_cvt_pk_bf16_f32 v9, v10, v11
	v_cvt_pk_bf16_f32 v10, v0, v1
	v_cvt_pk_bf16_f32 v11, v2, v3
	s_nop 1
	v_permlane16_swap_b32_e32 v8, v10
	v_permlane16_swap_b32_e32 v9, v11
	global_store_dwordx4 v[142:143], v[8:11], off offset:320
	s_branch .LBB0_527
.LBB0_619:
	s_branch .Lg3_ps
	v_cndmask_b32_e64 v128, 0, 1, s[38:39]
	v_cmp_ne_u32_e64 s[0:1], 1, v128
	s_andn2_b64 vcc, exec, s[38:39]
	s_cbranch_vccnz .LBB0_621
	v_mul_f32_e32 v128, 0xbfb8aa3b, v124
	v_mul_f32_e32 v129, 0xbfb8aa3b, v125
	v_mul_f32_e32 v130, 0xbfb8aa3b, v126
	v_mul_f32_e32 v131, 0xbfb8aa3b, v127
	v_exp_f32_e32 v128, v128
	v_exp_f32_e32 v129, v129
	v_exp_f32_e32 v130, v130
	v_exp_f32_e32 v131, v131
	v_add_f32_e32 v128, 1.0, v128
	v_add_f32_e32 v129, 1.0, v129
	v_add_f32_e32 v130, 1.0, v130
	v_add_f32_e32 v131, 1.0, v131
	v_rcp_f32_e32 v128, v128
	v_rcp_f32_e32 v130, v130
	v_rcp_f32_e32 v131, v131
	v_rcp_f32_e32 v129, v129
	v_pk_mul_f32 v[126:127], v[126:127], v[130:131]
	v_pk_mul_f32 v[124:125], v[124:125], v[128:129]
